# grid barrier: non-leader workgroups poll the top generation word directly (one hop less); prologue transposes remapped
# baseline (speedup 1.0000x reference)
.LBB0_57:
	s_sub_i32 s6, s0, s6
	s_add_i32 s6, s6, -1
	s_cmp_lg_u64 s[56:57], 0
	v_writelane_b32 v252, s0, 33
	s_cselect_b64 s[36:37], -1, 0
	v_cndmask_b32_e64 v223, 0, 1, s[36:37]
	v_writelane_b32 v252, s1, 34
	s_cmpk_gt_i32 s6, 0x18ff
	s_cbranch_scc1 .LBB0_207
	v_lshlrev_b32_e32 v2, 3, v1
	s_mulk_i32 s3, 0x4100
	v_lshrrev_b32_e32 v12, 3, v1
	v_and_b32_e32 v2, 56, v2
	s_add_i32 s0, s3, 0
	v_mul_u32_u24_e32 v3, 0x104, v2
	v_lshlrev_b32_e32 v4, 2, v12
	v_add3_u32 v13, s0, v3, v4
	v_lshlrev_b32_e32 v2, 1, v2
	v_mov_b32_e32 v3, 0
	v_lshl_add_u32 v11, v1, 2, s0
	v_lshl_add_u64 v[4:5], s[38:39], 0, v[2:3]
	s_mov_b64 s[0:1], 0x400000
	v_lshl_add_u64 v[4:5], v[4:5], 0, s[0:1]
	v_readlane_b32 s0, v252, 33
	s_lshl_b32 s3, s6, 6
	s_lshl_b32 s7, s0, 6
	s_movk_i32 s8, 0x5ff
	s_movk_i32 s9, 0x110f
	v_mov_b32_e32 v14, 0xc440
	s_movk_i32 s10, 0x7fff
	s_mov_b32 s11, 0xffff0000
	v_readlane_b32 s1, v252, 34
	s_branch .LBB0_60

.LBB0_990:
	s_or_b64 exec, exec, s[6:7]
	v_cvt_f32_u32_e32 v5, v3
	s_waitcnt vmcnt(0)
	v_readfirstlane_b32 s1, v4
	v_sub_u32_e32 v4, 0, v3
	v_rcp_iflag_f32_e32 v5, v5
	v_add_u32_e32 v6, s1, v0
	v_mul_f32_e32 v5, 0x4f7ffffe, v5
	v_cvt_u32_f32_e32 v5, v5
	v_mul_lo_u32 v0, v4, v5
	v_mul_hi_u32 v0, v5, v0
	v_add_u32_e32 v0, v5, v0
	v_mul_hi_u32 v0, v6, v0
	v_mul_lo_u32 v4, v0, v3
	v_sub_u32_e32 v4, v6, v4
	v_add_u32_e32 v5, 1, v0
	v_cmp_ge_u32_e32 vcc, v4, v3
	s_nop 1
	v_cndmask_b32_e32 v0, v0, v5, vcc
	v_sub_u32_e32 v5, v4, v3
	v_cndmask_b32_e32 v4, v4, v5, vcc
	v_add_u32_e32 v5, 1, v0
	v_cmp_ge_u32_e32 vcc, v4, v3
	v_add_u32_e32 v4, 1, v6
	s_nop 0
	v_cndmask_b32_e32 v0, v0, v5, vcc
	v_mul_lo_u32 v5, v3, v0
	v_add_u32_e32 v3, v5, v3
	v_cmp_ne_u32_e32 vcc, v4, v3
	s_and_saveexec_b64 s[6:7], vcc
	s_xor_b64 s[6:7], exec, s[6:7]
	s_cbranch_execz .LBB0_1004
	v_readlane_b32 s10, v253, 51
	v_readlane_b32 s11, v253, 52
	s_waitcnt lgkmcnt(0)
	s_nop 3
	global_load_dword v2, v1, s[10:11] sc1
	s_waitcnt vmcnt(0)
	v_cmp_eq_u32_e32 vcc, v2, v0
	s_and_saveexec_b64 s[38:39], vcc
	s_cbranch_execz .LBB0_1003
	s_mov_b32 s1, 1
	s_mov_b64 s[40:41], 0
	s_branch .LBB0_994

.LBB0_1159:
	s_or_b64 exec, exec, s[4:5]
	v_cvt_f32_u32_e32 v5, v3
	s_waitcnt vmcnt(0)
	v_readfirstlane_b32 s4, v4
	v_sub_u32_e32 v4, 0, v3
	v_rcp_iflag_f32_e32 v5, v5
	v_add_u32_e32 v6, s4, v0
	v_mul_f32_e32 v5, 0x4f7ffffe, v5
	v_cvt_u32_f32_e32 v5, v5
	v_mul_lo_u32 v0, v4, v5
	v_mul_hi_u32 v0, v5, v0
	v_add_u32_e32 v0, v5, v0
	v_mul_hi_u32 v0, v6, v0
	v_mul_lo_u32 v4, v0, v3
	v_sub_u32_e32 v4, v6, v4
	v_add_u32_e32 v5, 1, v0
	v_cmp_ge_u32_e32 vcc, v4, v3
	s_nop 1
	v_cndmask_b32_e32 v0, v0, v5, vcc
	v_sub_u32_e32 v5, v4, v3
	v_cndmask_b32_e32 v4, v4, v5, vcc
	v_add_u32_e32 v5, 1, v0
	v_cmp_ge_u32_e32 vcc, v4, v3
	v_add_u32_e32 v4, 1, v6
	s_nop 0
	v_cndmask_b32_e32 v0, v0, v5, vcc
	v_mul_lo_u32 v5, v3, v0
	v_add_u32_e32 v3, v5, v3
	v_cmp_ne_u32_e32 vcc, v4, v3
	s_and_saveexec_b64 s[4:5], vcc
	s_xor_b64 s[4:5], exec, s[4:5]
	s_cbranch_execz .LBB0_1173
	v_readlane_b32 s6, v253, 51
	v_readlane_b32 s7, v253, 52
	s_waitcnt lgkmcnt(0)
	s_nop 3
	global_load_dword v2, v1, s[6:7] sc1
	s_waitcnt vmcnt(0)
	v_cmp_eq_u32_e32 vcc, v2, v0
	s_and_saveexec_b64 s[6:7], vcc
	s_cbranch_execz .LBB0_1172
	s_mov_b32 s8, 1
	s_mov_b64 s[38:39], 0
	s_branch .LBB0_1163
